# modulated rmsnorm loops (norm1, norm2): 4 row loads and 12 parameter loads per token issued together instead of 5 serialized round trips; arithmetic order unchanged
# speedup vs baseline: 1.0722x; 1.0053x over previous
.LBB0_218:
	global_load_dwordx4 v[12:15], v[18:19], off offset:-3072
	global_load_dwordx4 v[8:11], v[18:19], off offset:-2048
	global_load_dwordx4 v[4:7], v[18:19], off offset:-1024
	global_load_dwordx4 v[0:3], v[18:19], off
	v_add_u32_e32 v180, 0xfffff000, v29
	v_ashrrev_i32_e32 v180, 12, v180
	v_mad_i32_i24 v180, v180, s81, s81
	v_cmp_lt_i32_e32 vcc, s82, v29
	v_mov_b32_e32 v27, v129
	v_mov_b32_e32 v25, v129
	s_nop 1
	v_cndmask_b32_e32 v180, 0, v180, vcc
	v_ashrrev_i32_e32 v181, 31, v180
	v_lshl_add_u64 v[32:33], v[180:181], 2, s[6:7]
	v_lshl_add_u64 v[30:31], v[32:33], 0, s[18:19]
	v_lshl_add_u64 v[182:183], v[30:31], 0, v[128:129]
	v_lshl_add_u64 v[32:33], v[32:33], 0, v[128:129]
	global_load_dwordx4 v[130:133], v[16:17], off
	global_load_dwordx4 v[146:149], v[182:183], off
	global_load_dwordx4 v[162:165], v[32:33], off
	global_load_dwordx4 v[134:137], v[16:17], off offset:1024
	global_load_dwordx4 v[150:153], v[182:183], off offset:1024
	global_load_dwordx4 v[166:169], v[32:33], off offset:1024
	global_load_dwordx4 v[138:141], v[16:17], off offset:2048
	global_load_dwordx4 v[154:157], v[182:183], off offset:2048
	global_load_dwordx4 v[170:173], v[32:33], off offset:2048
	global_load_dwordx4 v[142:145], v[16:17], off offset:3072
	global_load_dwordx4 v[158:161], v[182:183], off offset:3072
	global_load_dwordx4 v[174:177], v[32:33], off offset:3072
	v_lshl_add_u64 v[18:19], v[18:19], 0, s[76:77]
	s_waitcnt vmcnt(14)
	v_mov_b32_e32 v184, v13
	v_mov_b32_e32 v185, v9
	v_mov_b32_e32 v186, v12
	v_mov_b32_e32 v187, v8
	v_pk_mul_f32 v[184:185], v[184:185], v[184:185]
	s_nop 0
	v_pk_fma_f32 v[186:187], v[186:187], v[186:187], v[184:185]
	v_mov_b32_e32 v184, v14
	v_mov_b32_e32 v185, v10
	v_pk_fma_f32 v[186:187], v[184:185], v[184:185], v[186:187]
	v_mov_b32_e32 v184, v15
	v_mov_b32_e32 v185, v11
	v_pk_fma_f32 v[188:189], v[184:185], v[184:185], v[186:187]
	s_nop 0
	v_add_f32_e32 v23, v188, v189
	s_waitcnt vmcnt(12)
	v_mov_b32_e32 v42, v5
	v_mov_b32_e32 v43, v1
	v_mov_b32_e32 v40, v4
	v_mov_b32_e32 v41, v0
	v_pk_mul_f32 v[42:43], v[42:43], v[42:43]
	s_nop 0
	v_pk_fma_f32 v[40:41], v[40:41], v[40:41], v[42:43]
	v_mov_b32_e32 v42, v6
	v_mov_b32_e32 v43, v2
	v_pk_fma_f32 v[40:41], v[42:43], v[42:43], v[40:41]
	v_mov_b32_e32 v42, v7
	v_mov_b32_e32 v43, v3
	v_pk_fma_f32 v[40:41], v[42:43], v[42:43], v[40:41]
	s_nop 0
	v_add_f32_e32 v23, v23, v40
	v_add_f32_e32 v23, v23, v41
	ds_bpermute_b32 v25, v34, v23
	s_waitcnt lgkmcnt(0)
	v_add_f32_e32 v23, v23, v25
	ds_bpermute_b32 v25, v35, v23
	s_waitcnt lgkmcnt(0)
	v_add_f32_e32 v23, v23, v25
	ds_bpermute_b32 v25, v36, v23
	s_waitcnt lgkmcnt(0)
	v_add_f32_e32 v23, v23, v25
	ds_bpermute_b32 v25, v37, v23
	s_waitcnt lgkmcnt(0)
	v_add_f32_e32 v23, v23, v25
	ds_bpermute_b32 v25, v38, v23
	s_waitcnt lgkmcnt(0)
	v_add_f32_e32 v23, v23, v25
	ds_bpermute_b32 v25, v39, v23
	s_waitcnt lgkmcnt(0)
	v_add_f32_e32 v23, v23, v25
	v_fmamk_f32 v23, v23, 0x3a800000, v206
	v_cmp_gt_f32_e32 vcc, s83, v23
	v_mul_f32_e32 v25, 0x4b800000, v23
	s_nop 0
	v_cndmask_b32_e32 v23, v23, v25, vcc
	v_rsq_f32_e32 v23, v23
	s_nop 0
	v_mul_f32_e32 v25, 0x45800000, v23
	v_cndmask_b32_e32 v28, v23, v25, vcc
	v_mov_b32_e32 v23, v129
	v_mov_b32_e32 v25, v129
	v_pk_mul_f32 v[12:13], v[12:13], v[28:29] op_sel_hi:[1,0]
	v_pk_mul_f32 v[14:15], v[14:15], v[28:29] op_sel_hi:[1,0]
	v_pk_mul_f32 v[8:9], v[8:9], v[28:29] op_sel_hi:[1,0]
	v_pk_mul_f32 v[10:11], v[10:11], v[28:29] op_sel_hi:[1,0]
	v_pk_mul_f32 v[4:5], v[4:5], v[28:29] op_sel_hi:[1,0]
	v_pk_mul_f32 v[6:7], v[6:7], v[28:29] op_sel_hi:[1,0]
	v_pk_mul_f32 v[0:1], v[0:1], v[28:29] op_sel_hi:[1,0]
	v_pk_mul_f32 v[2:3], v[2:3], v[28:29] op_sel_hi:[1,0]
	v_add_u32_e32 v29, s66, v29
	v_cmp_lt_i32_e32 vcc, s84, v29
	s_or_b64 s[8:9], vcc, s[8:9]
	s_waitcnt vmcnt(0)
	v_pk_mul_f32 v[12:13], v[130:131], v[12:13]
	v_pk_add_f32 v[40:41], v[146:147], 1.0 op_sel_hi:[1,0]
	v_pk_mul_f32 v[14:15], v[132:133], v[14:15]
	v_pk_fma_f32 v[12:13], v[40:41], v[12:13], v[162:163]
	v_pk_add_f32 v[40:41], v[148:149], 1.0 op_sel_hi:[1,0]
	v_cvt_pk_bf16_f32 v12, v12, v13
	v_pk_fma_f32 v[14:15], v[40:41], v[14:15], v[164:165]
	s_nop 0
	v_cvt_pk_bf16_f32 v13, v14, v15
	global_store_dwordx2 v[20:21], v[12:13], off offset:-1024
	v_pk_mul_f32 v[8:9], v[134:135], v[8:9]
	v_pk_add_f32 v[40:41], v[150:151], 1.0 op_sel_hi:[1,0]
	v_pk_mul_f32 v[10:11], v[136:137], v[10:11]
	v_pk_fma_f32 v[8:9], v[40:41], v[8:9], v[166:167]
	v_pk_add_f32 v[40:41], v[152:153], 1.0 op_sel_hi:[1,0]
	v_cvt_pk_bf16_f32 v8, v8, v9
	v_pk_fma_f32 v[10:11], v[40:41], v[10:11], v[168:169]
	s_nop 0
	v_cvt_pk_bf16_f32 v9, v10, v11
	global_store_dwordx2 v[20:21], v[8:9], off offset:-512
	v_pk_mul_f32 v[4:5], v[138:139], v[4:5]
	v_pk_add_f32 v[40:41], v[154:155], 1.0 op_sel_hi:[1,0]
	v_pk_mul_f32 v[6:7], v[140:141], v[6:7]
	v_pk_fma_f32 v[4:5], v[40:41], v[4:5], v[170:171]
	v_pk_add_f32 v[40:41], v[156:157], 1.0 op_sel_hi:[1,0]
	v_cvt_pk_bf16_f32 v4, v4, v5
	v_pk_fma_f32 v[6:7], v[40:41], v[6:7], v[172:173]
	s_nop 0
	v_cvt_pk_bf16_f32 v5, v6, v7
	global_store_dwordx2 v[20:21], v[4:5], off
	v_pk_mul_f32 v[0:1], v[142:143], v[0:1]
	v_pk_add_f32 v[40:41], v[158:159], 1.0 op_sel_hi:[1,0]
	v_pk_mul_f32 v[2:3], v[144:145], v[2:3]
	v_pk_fma_f32 v[0:1], v[40:41], v[0:1], v[174:175]
	v_pk_add_f32 v[40:41], v[160:161], 1.0 op_sel_hi:[1,0]
	v_cvt_pk_bf16_f32 v0, v0, v1
	v_pk_fma_f32 v[2:3], v[40:41], v[2:3], v[176:177]
	s_nop 0
	v_cvt_pk_bf16_f32 v1, v2, v3
	global_store_dwordx2 v[20:21], v[0:1], off offset:512
	v_lshl_add_u64 v[20:21], v[20:21], 0, s[38:39]
	s_andn2_b64 exec, exec, s[8:9]
	s_cbranch_execnz .LBB0_218

.LBB0_1993:
	global_load_dwordx4 v[12:15], v[18:19], off offset:-3072
	global_load_dwordx4 v[8:11], v[18:19], off offset:-2048
	global_load_dwordx4 v[4:7], v[18:19], off offset:-1024
	global_load_dwordx4 v[0:3], v[18:19], off
	v_add_u32_e32 v180, 0xfffff000, v29
	v_ashrrev_i32_e32 v180, 12, v180
	v_mad_i32_i24 v180, v180, s81, s81
	v_cmp_lt_i32_e32 vcc, s82, v29
	v_mov_b32_e32 v27, v129
	v_mov_b32_e32 v25, v129
	s_nop 1
	v_cndmask_b32_e32 v180, 0, v180, vcc
	v_ashrrev_i32_e32 v181, 31, v180
	v_lshl_add_u64 v[32:33], v[180:181], 2, s[8:9]
	v_lshl_add_u64 v[30:31], v[32:33], 0, s[36:37]
	v_lshl_add_u64 v[182:183], v[30:31], 0, v[128:129]
	v_lshl_add_u64 v[32:33], v[32:33], 0, v[128:129]
	global_load_dwordx4 v[130:133], v[16:17], off
	global_load_dwordx4 v[146:149], v[182:183], off
	global_load_dwordx4 v[162:165], v[32:33], off
	global_load_dwordx4 v[134:137], v[16:17], off offset:1024
	global_load_dwordx4 v[150:153], v[182:183], off offset:1024
	global_load_dwordx4 v[166:169], v[32:33], off offset:1024
	global_load_dwordx4 v[138:141], v[16:17], off offset:2048
	global_load_dwordx4 v[154:157], v[182:183], off offset:2048
	global_load_dwordx4 v[170:173], v[32:33], off offset:2048
	global_load_dwordx4 v[142:145], v[16:17], off offset:3072
	global_load_dwordx4 v[158:161], v[182:183], off offset:3072
	global_load_dwordx4 v[174:177], v[32:33], off offset:3072
	v_lshl_add_u64 v[18:19], v[18:19], 0, s[76:77]
	s_waitcnt vmcnt(14)
	v_mov_b32_e32 v184, v13
	v_mov_b32_e32 v185, v9
	v_mov_b32_e32 v186, v12
	v_mov_b32_e32 v187, v8
	v_pk_mul_f32 v[184:185], v[184:185], v[184:185]
	s_nop 0
	v_pk_fma_f32 v[186:187], v[186:187], v[186:187], v[184:185]
	v_mov_b32_e32 v184, v14
	v_mov_b32_e32 v185, v10
	v_pk_fma_f32 v[186:187], v[184:185], v[184:185], v[186:187]
	v_mov_b32_e32 v184, v15
	v_mov_b32_e32 v185, v11
	v_pk_fma_f32 v[188:189], v[184:185], v[184:185], v[186:187]
	s_nop 0
	v_add_f32_e32 v23, v188, v189
	s_waitcnt vmcnt(12)
	v_mov_b32_e32 v42, v5
	v_mov_b32_e32 v43, v1
	v_mov_b32_e32 v40, v4
	v_mov_b32_e32 v41, v0
	v_pk_mul_f32 v[42:43], v[42:43], v[42:43]
	s_nop 0
	v_pk_fma_f32 v[40:41], v[40:41], v[40:41], v[42:43]
	v_mov_b32_e32 v42, v6
	v_mov_b32_e32 v43, v2
	v_pk_fma_f32 v[40:41], v[42:43], v[42:43], v[40:41]
	v_mov_b32_e32 v42, v7
	v_mov_b32_e32 v43, v3
	v_pk_fma_f32 v[40:41], v[42:43], v[42:43], v[40:41]
	s_nop 0
	v_add_f32_e32 v23, v23, v40
	v_add_f32_e32 v23, v23, v41
	ds_bpermute_b32 v25, v34, v23
	s_waitcnt lgkmcnt(0)
	v_add_f32_e32 v23, v23, v25
	ds_bpermute_b32 v25, v35, v23
	s_waitcnt lgkmcnt(0)
	v_add_f32_e32 v23, v23, v25
	ds_bpermute_b32 v25, v36, v23
	s_waitcnt lgkmcnt(0)
	v_add_f32_e32 v23, v23, v25
	ds_bpermute_b32 v25, v37, v23
	s_waitcnt lgkmcnt(0)
	v_add_f32_e32 v23, v23, v25
	ds_bpermute_b32 v25, v38, v23
	s_waitcnt lgkmcnt(0)
	v_add_f32_e32 v23, v23, v25
	ds_bpermute_b32 v25, v39, v23
	s_waitcnt lgkmcnt(0)
	v_add_f32_e32 v23, v23, v25
	v_fmamk_f32 v23, v23, 0x3a800000, v206
	v_cmp_gt_f32_e32 vcc, s83, v23
	v_mul_f32_e32 v25, 0x4b800000, v23
	s_nop 0
	v_cndmask_b32_e32 v23, v23, v25, vcc
	v_rsq_f32_e32 v23, v23
	s_nop 0
	v_mul_f32_e32 v25, 0x45800000, v23
	v_cndmask_b32_e32 v28, v23, v25, vcc
	v_mov_b32_e32 v23, v129
	v_mov_b32_e32 v25, v129
	v_pk_mul_f32 v[12:13], v[12:13], v[28:29] op_sel_hi:[1,0]
	v_pk_mul_f32 v[14:15], v[14:15], v[28:29] op_sel_hi:[1,0]
	v_pk_mul_f32 v[8:9], v[8:9], v[28:29] op_sel_hi:[1,0]
	v_pk_mul_f32 v[10:11], v[10:11], v[28:29] op_sel_hi:[1,0]
	v_pk_mul_f32 v[4:5], v[4:5], v[28:29] op_sel_hi:[1,0]
	v_pk_mul_f32 v[6:7], v[6:7], v[28:29] op_sel_hi:[1,0]
	v_pk_mul_f32 v[0:1], v[0:1], v[28:29] op_sel_hi:[1,0]
	v_pk_mul_f32 v[2:3], v[2:3], v[28:29] op_sel_hi:[1,0]
	v_add_u32_e32 v29, s66, v29
	v_cmp_lt_i32_e32 vcc, s84, v29
	s_or_b64 s[10:11], vcc, s[10:11]
	s_waitcnt vmcnt(0)
	v_pk_mul_f32 v[12:13], v[130:131], v[12:13]
	v_pk_add_f32 v[40:41], v[146:147], 1.0 op_sel_hi:[1,0]
	v_pk_mul_f32 v[14:15], v[132:133], v[14:15]
	v_pk_fma_f32 v[12:13], v[40:41], v[12:13], v[162:163]
	v_pk_add_f32 v[40:41], v[148:149], 1.0 op_sel_hi:[1,0]
	v_cvt_pk_bf16_f32 v12, v12, v13
	v_pk_fma_f32 v[14:15], v[40:41], v[14:15], v[164:165]
	s_nop 0
	v_cvt_pk_bf16_f32 v13, v14, v15
	global_store_dwordx2 v[20:21], v[12:13], off offset:-1024
	v_pk_mul_f32 v[8:9], v[134:135], v[8:9]
	v_pk_add_f32 v[40:41], v[150:151], 1.0 op_sel_hi:[1,0]
	v_pk_mul_f32 v[10:11], v[136:137], v[10:11]
	v_pk_fma_f32 v[8:9], v[40:41], v[8:9], v[166:167]
	v_pk_add_f32 v[40:41], v[152:153], 1.0 op_sel_hi:[1,0]
	v_cvt_pk_bf16_f32 v8, v8, v9
	v_pk_fma_f32 v[10:11], v[40:41], v[10:11], v[168:169]
	s_nop 0
	v_cvt_pk_bf16_f32 v9, v10, v11
	global_store_dwordx2 v[20:21], v[8:9], off offset:-512
	v_pk_mul_f32 v[4:5], v[138:139], v[4:5]
	v_pk_add_f32 v[40:41], v[154:155], 1.0 op_sel_hi:[1,0]
	v_pk_mul_f32 v[6:7], v[140:141], v[6:7]
	v_pk_fma_f32 v[4:5], v[40:41], v[4:5], v[170:171]
	v_pk_add_f32 v[40:41], v[156:157], 1.0 op_sel_hi:[1,0]
	v_cvt_pk_bf16_f32 v4, v4, v5
	v_pk_fma_f32 v[6:7], v[40:41], v[6:7], v[172:173]
	s_nop 0
	v_cvt_pk_bf16_f32 v5, v6, v7
	global_store_dwordx2 v[20:21], v[4:5], off
	v_pk_mul_f32 v[0:1], v[142:143], v[0:1]
	v_pk_add_f32 v[40:41], v[158:159], 1.0 op_sel_hi:[1,0]
	v_pk_mul_f32 v[2:3], v[144:145], v[2:3]
	v_pk_fma_f32 v[0:1], v[40:41], v[0:1], v[174:175]
	v_pk_add_f32 v[40:41], v[160:161], 1.0 op_sel_hi:[1,0]
	v_cvt_pk_bf16_f32 v0, v0, v1
	v_pk_fma_f32 v[2:3], v[40:41], v[2:3], v[176:177]
	s_nop 0
	v_cvt_pk_bf16_f32 v1, v2, v3
	global_store_dwordx2 v[20:21], v[0:1], off offset:512
	v_lshl_add_u64 v[20:21], v[20:21], 0, s[38:39]
	s_andn2_b64 exec, exec, s[10:11]
	s_cbranch_execnz .LBB0_1993
